# v24: SWA rope one wave per SIMD on all CUs (item=blockIdx, quarter=wave); OUT epilogue round-2 parameter loads issued with round 1
# speedup vs baseline: 1.0063x; 1.0063x over previous
; #define PHASE_IDS() int lane_; asm volatile("v_mbcnt_lo_u32_b32 %0, -1, 0\n\tv_mbcnt_hi_u32_b32 %0, -1, %0" : "=v"(lane_)); const int lane = lane_, wave = wave_s; int gw_ = (int)blockIdx.x * NWAVES + wave; asm volatile("" : "+s"(gw_)); const int gw = gw_; const int x32 = (lane ^ 32) << 2; (void)gw; (void)lane; (void)x32
; DI void rope_phase(bf16* qb, unsigned char* kfb, int nkv, const float* gains, bool do_kmean, bf16* kmean, int NGW, const int wave_s) {
;     const int nslots = nkv;
;     PHASE_IDS();
;     const int sub = lane >> 3, j = lane & 7;
;     float invf[8];
; #pragma unroll
;     for (int t = 0; t < 8; ++t) invf[t] = exp2f(-(float)(8 * (j & 3) + t) * (13.287712379549449f / 32.f));
;     for (int id = gw; id < NB * 16 * nslots; id += NGW) {
;         const int slot = 16 + id % nslots, bn = id / nslots, b = bn >> 4, n = bn & 15;
.LBB0_397:
	s_mov_b64 s[14:15], s[0:1]
	v_readlane_b32 s22, v242, 4
	s_lshl_b32 s23, s40, 7
	s_mov_b32 s98, 0
	s_mov_b32 s99, -8
	s_cmp_lg_u32 s40, 2
	s_cbranch_scc1 .Lrope_full
	s_lshl_b32 s98, s33, 6
	s_mov_b32 s99, 16
	s_mov_b32 s22, s2
	s_cmp_lt_u32 s33, 4
	s_cbranch_scc1 .Lrope_full
	s_mov_b32 s22, 0x7fffffff

;     __device__ __forceinline__ void operator()(const f32x4 (&acc)[2][2][4][2], const Unit& u, int wr, int wc, int fr, int fq) const {
;     ...
;         for (int bj = 0; bj < 2; ++bj) { const int col = col0 + bj * HALF;
;             const f32x4 g0 = *(const f32x4*)(gate + (size_t)bb * 6144 + col), g1 = *(const f32x4*)(gate + (size_t)bb * 6144 + col + 4);
;             f32x4 c0 = *(const f32x4*)(gain_c + col) * (*(const f32x4*)(sc_c + (size_t)bb * 6144 + col) + 1.f), c1 = *(const f32x4*)(gain_c + col + 4) * (*(const f32x4*)(sc_c + (size_t)bb * 6144 + col + 4) + 1.f);
; #pragma unroll
;             for (int e = 0; e < 4; ++e) { c0[e] = __builtin_amdgcn_rcpf(c0[e]); c1[e] = __builtin_amdgcn_rcpf(c1[e]); }
;             f32x4 n0 = c0, n1 = c1;
;             if (xs) { n0 = *(const f32x4*)(gain_n + col) * (*(const f32x4*)(sc_n + (size_t)bb * 6144 + col) + 1.f); n1 = *(const f32x4*)(gain_n + col + 4) * (*(const f32x4*)(sc_n + (size_t)bb * 6144 + col + 4) + 1.f); }
; #pragma unroll
;             for (int ai = 0; ai < 2; ++ai)
; #pragma unroll
;                 for (int m = 0; m < 4; ++m) { const size_t e0 = (size_t)(row0 + ai * HALF + m * 16) * 1024 + col;
;                     const u32x4 r = *(const u32x4*)(xs_in + e0);
;                     const f32x4 x0 = (f32x4){__builtin_bit_cast(float, r.x << 16), __builtin_bit_cast(float, r.x & 0xffff0000u), __builtin_bit_cast(float, r.y << 16), __builtin_bit_cast(float, r.y & 0xffff0000u)} * c0;
;                     const f32x4 x1 = (f32x4){__builtin_bit_cast(float, r.z << 16), __builtin_bit_cast(float, r.z & 0xffff0000u), __builtin_bit_cast(float, r.w << 16), __builtin_bit_cast(float, r.w & 0xffff0000u)} * c1;
;                     const f32x4 y0 = x0 + g0 * acc[ai][bj][m][0], y1 = x1 + g1 * acc[ai][bj][m][1];
;                     if (fout) { __builtin_nontemporal_store(y0, (f32x4*)(fout + e0)); __builtin_nontemporal_store(y1, (f32x4*)(fout + e0 + 4)); }
;                     if (xs) { const f32x4 z0 = y0 * n0, z1 = y1 * n1;
;                         u32x4 w; w.x = cvt_pk_bf16(z0[0], z0[1]); w.y = cvt_pk_bf16(z0[2], z0[3]); w.z = cvt_pk_bf16(z1[0], z1[1]); w.w = cvt_pk_bf16(z1[2], z1[3]);
;                         *(u32x4*)(xs + e0) = w;
;                         ssq[ai * 4 + m] += (y0[0] * y0[0] + y0[1] * y0[1]) + (y0[2] * y0[2] + y0[3] * y0[3]) + (y1[0] * y1[0] + y1[1] * y1[1]) + (y1[2] * y1[2] + y1[3] * y1[3]); } } }
.LBB0_661:
	s_ashr_i32 s25, s65, 4
	v_lshl_or_b32 v166, s64, 8, v197
	s_mul_hi_i32 s27, s25, 0x6000
	s_mulk_i32 s25, 0x6000
	s_add_u32 s34, s8, s25
	v_ashrrev_i32_e32 v167, 31, v166
	s_addc_u32 s35, s9, s27
	v_lshlrev_b64 v[150:151], 2, v[166:167]
	v_lshl_add_u64 v[168:169], s[34:35], 0, v[150:151]
	s_add_u32 s34, s94, s25
	s_addc_u32 s35, s95, s27
	v_lshl_add_u64 v[170:171], s[14:15], 0, v[150:151]
	v_lshl_add_u64 v[152:153], s[34:35], 0, v[150:151]
	global_load_dwordx4 v[94:97], v[168:169], off offset:16
	global_load_dwordx4 v[98:101], v[168:169], off
	global_load_dwordx4 v[162:165], v[170:171], off offset:16
	global_load_dwordx4 v[172:175], v[170:171], off
	global_load_dwordx4 v[176:179], v[152:153], off offset:16
	global_load_dwordx4 v[180:183], v[152:153], off
	s_add_u32 s34, s46, s25
	s_addc_u32 s35, s47, s27
	v_lshl_add_u32 v148, s65, 8, v194
	v_ashrrev_i32_e32 v149, 31, v148
	v_lshl_add_u32 v243, v148, 10, v166
	v_lshlrev_b32_e32 v243, 1, v243
	global_load_dwordx4 v[220:223], v243, s[12:13]
	v_add_u32_e32 v241, 0x8000, v243
	global_load_dwordx4 v[224:227], v241, s[12:13]
	v_add_u32_e32 v240, 0x10000, v243
	global_load_dwordx4 v[228:231], v240, s[12:13]
	v_add_u32_e32 v241, 0x18000, v243
	global_load_dwordx4 v[232:235], v241, s[12:13]
	v_add_u32_e32 v240, 0x40000, v243
	global_load_dwordx4 v[236:239], v240, s[12:13]
	v_add_u32_e32 v241, 0x48000, v243
	global_load_dwordx4 v[244:247], v241, s[12:13]
	v_add_u32_e32 v240, 0x50000, v243
	global_load_dwordx4 v[248:251], v240, s[12:13]
	v_add_u32_e32 v241, 0x58000, v243
	global_load_dwordx4 v[252:255], v241, s[12:13]
	global_load_dwordx4 v[216:219], v150, s[18:19] offset:16
	global_load_dwordx4 v[188:191], v150, s[18:19]
	global_load_dwordx4 v[200:203], v150, s[34:35] offset:16
	global_load_dwordx4 v[210:213], v150, s[34:35]
	s_waitcnt vmcnt(0)
	v_pk_add_f32 v[176:177], v[176:177], 1.0 op_sel_hi:[1,0]
	v_pk_add_f32 v[182:183], v[182:183], 1.0 op_sel_hi:[1,0]
	v_pk_add_f32 v[180:181], v[180:181], 1.0 op_sel_hi:[1,0]
	v_pk_add_f32 v[178:179], v[178:179], 1.0 op_sel_hi:[1,0]
	v_pk_mul_f32 v[162:163], v[162:163], v[176:177]
	v_pk_mul_f32 v[174:175], v[174:175], v[182:183]
	v_pk_mul_f32 v[172:173], v[172:173], v[180:181]
	v_pk_mul_f32 v[164:165], v[164:165], v[178:179]
	v_rcp_f32_e32 v178, v162
	v_rcp_f32_e32 v179, v163
	v_lshl_add_u64 v[162:163], s[18:19], 0, v[150:151]
	v_lshl_add_u64 v[150:151], s[34:35], 0, v[150:151]
	v_rcp_f32_e32 v182, v172
	v_rcp_f32_e32 v183, v173
	v_rcp_f32_e32 v184, v174
	v_rcp_f32_e32 v185, v175
	v_mov_b32_e32 v172, v216
	v_mov_b32_e32 v173, v217
	v_mov_b32_e32 v174, v218
	v_mov_b32_e32 v175, v219
	v_rcp_f32_e32 v180, v164
	v_rcp_f32_e32 v181, v165
	s_mov_b64 s[34:35], 0x20000
	v_pk_add_f32 v[164:165], v[212:213], 1.0 op_sel_hi:[1,0]
	v_pk_add_f32 v[176:177], v[210:211], 1.0 op_sel_hi:[1,0]
	v_pk_mul_f32 v[186:187], v[190:191], v[164:165]
	v_pk_add_f32 v[164:165], v[202:203], 1.0 op_sel_hi:[1,0]
	v_pk_mul_f32 v[188:189], v[188:189], v[176:177]
	v_pk_add_f32 v[176:177], v[200:201], 1.0 op_sel_hi:[1,0]
	v_pk_mul_f32 v[190:191], v[174:175], v[164:165]
	v_lshlrev_b64 v[164:165], 10, v[148:149]
	v_pk_mul_f32 v[192:193], v[172:173], v[176:177]
	v_lshl_add_u64 v[172:173], v[164:165], 0, v[166:167]
	v_lshlrev_b64 v[176:177], 1, v[172:173]
	v_lshl_add_u64 v[172:173], s[12:13], 0, v[176:177]
	v_lshl_add_u64 v[176:177], s[16:17], 0, v[176:177]
	s_waitcnt vmcnt(0)
	s_nop 1
	v_mov_b32_e32 v172, v220
	v_mov_b32_e32 v173, v221
	v_mov_b32_e32 v174, v222
	v_mov_b32_e32 v175, v223
	v_lshlrev_b32_e32 v200, 16, v172
	v_and_b32_e32 v201, 0xffff0000, v172
	v_lshlrev_b32_e32 v172, 16, v173
	v_and_b32_e32 v173, 0xffff0000, v173
	v_pk_mul_f32 v[200:201], v[182:183], v[200:201]
	v_lshlrev_b32_e32 v202, 16, v174
	v_and_b32_e32 v203, 0xffff0000, v174
	v_pk_mul_f32 v[172:173], v[184:185], v[172:173]
	v_lshlrev_b32_e32 v174, 16, v175
	v_and_b32_e32 v175, 0xffff0000, v175
	v_pk_mul_f32 v[202:203], v[178:179], v[202:203]
	v_pk_fma_f32 v[134:135], v[134:135], v[98:99], v[200:201]
	v_pk_mul_f32 v[174:175], v[180:181], v[174:175]
	v_pk_fma_f32 v[136:137], v[136:137], v[100:101], v[172:173]
	v_pk_fma_f32 v[172:173], v[130:131], v[94:95], v[202:203]
	v_pk_mul_f32 v[130:131], v[188:189], v[134:135]
	v_pk_fma_f32 v[174:175], v[132:133], v[96:97], v[174:175]
	v_pk_mul_f32 v[132:133], v[186:187], v[136:137]
	v_cvt_pk_bf16_f32 v130, v130, v131
	v_pk_mul_f32 v[200:201], v[190:191], v[174:175]
	v_cvt_pk_bf16_f32 v131, v132, v133
	v_pk_mul_f32 v[202:203], v[192:193], v[172:173]
	s_nop 0
	v_cvt_pk_bf16_f32 v132, v202, v203
	v_cvt_pk_bf16_f32 v133, v200, v201
	global_store_dwordx4 v[176:177], v[130:133], off
	s_nop 1
	v_mul_f32_e32 v130, v135, v135
	v_mul_f32_e32 v131, v137, v137
	v_fmac_f32_e32 v130, v134, v134
	v_fmac_f32_e32 v131, v136, v136
	v_add_f32_e32 v130, v130, v131
	v_mul_f32_e32 v131, v173, v173
	v_fmac_f32_e32 v131, v172, v172
	v_add_f32_e32 v130, v131, v130
	v_mul_f32_e32 v131, v175, v175
	v_fmac_f32_e32 v131, v174, v174
	v_add_f32_e32 v199, v131, v130
	v_or_b32_e32 v130, 16, v148
	v_ashrrev_i32_e32 v131, 31, v130
	v_lshlrev_b64 v[130:131], 10, v[130:131]
	v_lshl_add_u64 v[132:133], v[130:131], 0, v[166:167]
	v_lshlrev_b64 v[136:137], 1, v[132:133]
	v_lshl_add_u64 v[132:133], s[12:13], 0, v[136:137]
	v_lshl_add_u64 v[136:137], s[16:17], 0, v[136:137]
	s_nop 1
	v_mov_b32_e32 v132, v224
	v_mov_b32_e32 v133, v225
	v_mov_b32_e32 v134, v226
	v_mov_b32_e32 v135, v227
	v_lshlrev_b32_e32 v172, 16, v132
	v_and_b32_e32 v173, 0xffff0000, v132
	v_lshlrev_b32_e32 v132, 16, v133
	v_and_b32_e32 v133, 0xffff0000, v133
	v_pk_mul_f32 v[172:173], v[182:183], v[172:173]
	v_pk_mul_f32 v[132:133], v[184:185], v[132:133]
; __device__ __forceinline__ unsigned cvt_pk_bf16(float lo, float hi) { unsigned r; asm volatile("v_cvt_pk_bf16_f32 %0, %1, %2" : "=v"(r) : "v"(lo), "v"(hi)); return r; }
;     __device__ __forceinline__ void operator()(const f32x4 (&acc)[2][2][4][2], const Unit& u, int wr, int wc, int fr, int fq) const {
;     ...
;             for (int ai = 0; ai < 2; ++ai)
; #pragma unroll
;                 for (int m = 0; m < 4; ++m) { const size_t e0 = (size_t)(row0 + ai * HALF + m * 16) * 1024 + col;
;                     const u32x4 r = *(const u32x4*)(xs_in + e0);
;                     const f32x4 x0 = (f32x4){__builtin_bit_cast(float, r.x << 16), __builtin_bit_cast(float, r.x & 0xffff0000u), __builtin_bit_cast(float, r.y << 16), __builtin_bit_cast(float, r.y & 0xffff0000u)} * c0;
;                     const f32x4 x1 = (f32x4){__builtin_bit_cast(float, r.z << 16), __builtin_bit_cast(float, r.z & 0xffff0000u), __builtin_bit_cast(float, r.w << 16), __builtin_bit_cast(float, r.w & 0xffff0000u)} * c1;
;                     const f32x4 y0 = x0 + g0 * acc[ai][bj][m][0], y1 = x1 + g1 * acc[ai][bj][m][1];
;                     if (fout) { __builtin_nontemporal_store(y0, (f32x4*)(fout + e0)); __builtin_nontemporal_store(y1, (f32x4*)(fout + e0 + 4)); }
;                     if (xs) { const f32x4 z0 = y0 * n0, z1 = y1 * n1;
;                         u32x4 w; w.x = cvt_pk_bf16(z0[0], z0[1]); w.y = cvt_pk_bf16(z0[2], z0[3]); w.z = cvt_pk_bf16(z1[0], z1[1]); w.w = cvt_pk_bf16(z1[2], z1[3]);
;                         *(u32x4*)(xs + e0) = w;
;                         ssq[ai * 4 + m] += (y0[0] * y0[0] + y0[1] * y0[1]) + (y0[2] * y0[2] + y0[3] * y0[3]) + (y1[0] * y1[0] + y1[1] * y1[1]) + (y1[2] * y1[2] + y1[3] * y1[3]); } } }
	v_lshlrev_b32_e32 v174, 16, v134
	v_and_b32_e32 v175, 0xffff0000, v134
	v_lshlrev_b32_e32 v134, 16, v135
	v_and_b32_e32 v135, 0xffff0000, v135
	v_pk_fma_f32 v[126:127], v[126:127], v[98:99], v[172:173]
	v_pk_mul_f32 v[174:175], v[178:179], v[174:175]
	v_pk_mul_f32 v[134:135], v[180:181], v[134:135]
	v_pk_fma_f32 v[128:129], v[128:129], v[100:101], v[132:133]
	v_pk_mul_f32 v[132:133], v[188:189], v[126:127]
	v_pk_fma_f32 v[124:125], v[124:125], v[96:97], v[134:135]
	v_pk_fma_f32 v[122:123], v[122:123], v[94:95], v[174:175]
	v_pk_mul_f32 v[134:135], v[186:187], v[128:129]
	v_cvt_pk_bf16_f32 v132, v132, v133
	v_pk_mul_f32 v[172:173], v[190:191], v[124:125]
	v_pk_mul_f32 v[174:175], v[192:193], v[122:123]
	v_cvt_pk_bf16_f32 v133, v134, v135
	s_nop 0
	v_cvt_pk_bf16_f32 v134, v174, v175
	v_cvt_pk_bf16_f32 v135, v172, v173
	global_store_dwordx4 v[136:137], v[132:135], off
	s_nop 1
	v_or_b32_e32 v132, 32, v148
	v_ashrrev_i32_e32 v133, 31, v132
	v_lshlrev_b64 v[132:133], 10, v[132:133]
	v_lshl_add_u64 v[134:135], v[132:133], 0, v[166:167]
	v_lshlrev_b64 v[172:173], 1, v[134:135]
	v_lshl_add_u64 v[134:135], s[12:13], 0, v[172:173]
	v_lshl_add_u64 v[172:173], s[16:17], 0, v[172:173]
	s_nop 1
	v_mov_b32_e32 v134, v228
	v_mov_b32_e32 v135, v229
	v_mov_b32_e32 v136, v230
	v_mov_b32_e32 v137, v231
	v_lshlrev_b32_e32 v174, 16, v134
	v_and_b32_e32 v175, 0xffff0000, v134
	v_lshlrev_b32_e32 v134, 16, v135
	v_and_b32_e32 v135, 0xffff0000, v135
	v_pk_mul_f32 v[174:175], v[182:183], v[174:175]
	v_pk_mul_f32 v[134:135], v[184:185], v[134:135]
	v_lshlrev_b32_e32 v176, 16, v136
	v_and_b32_e32 v177, 0xffff0000, v136
	v_lshlrev_b32_e32 v136, 16, v137
	v_and_b32_e32 v137, 0xffff0000, v137
	v_pk_fma_f32 v[118:119], v[118:119], v[98:99], v[174:175]
	v_pk_mul_f32 v[176:177], v[178:179], v[176:177]
	v_pk_mul_f32 v[136:137], v[180:181], v[136:137]
	v_pk_fma_f32 v[120:121], v[120:121], v[100:101], v[134:135]
	v_pk_mul_f32 v[134:135], v[188:189], v[118:119]
	v_pk_fma_f32 v[116:117], v[116:117], v[96:97], v[136:137]
	v_pk_fma_f32 v[114:115], v[114:115], v[94:95], v[176:177]
	v_pk_mul_f32 v[136:137], v[186:187], v[120:121]
	v_cvt_pk_bf16_f32 v134, v134, v135
	v_pk_mul_f32 v[174:175], v[190:191], v[116:117]
	v_pk_mul_f32 v[176:177], v[192:193], v[114:115]
	v_cvt_pk_bf16_f32 v135, v136, v137
	s_nop 0
	v_cvt_pk_bf16_f32 v136, v176, v177
	v_cvt_pk_bf16_f32 v137, v174, v175
	global_store_dwordx4 v[172:173], v[134:137], off
	s_nop 1
	v_or_b32_e32 v134, 48, v148
	v_ashrrev_i32_e32 v135, 31, v134
	v_lshlrev_b64 v[134:135], 10, v[134:135]
	v_lshl_add_u64 v[136:137], v[134:135], 0, v[166:167]
	v_lshlrev_b64 v[136:137], 1, v[136:137]
	v_lshl_add_u64 v[172:173], s[12:13], 0, v[136:137]
	v_lshl_add_u64 v[136:137], s[16:17], 0, v[136:137]
	s_nop 1
	v_mov_b32_e32 v172, v232
	v_mov_b32_e32 v173, v233
	v_mov_b32_e32 v174, v234
	v_mov_b32_e32 v175, v235
	v_lshlrev_b32_e32 v176, 16, v172
	v_and_b32_e32 v177, 0xffff0000, v172
	v_lshlrev_b32_e32 v172, 16, v173
	v_and_b32_e32 v173, 0xffff0000, v173
	v_pk_mul_f32 v[176:177], v[182:183], v[176:177]
	v_pk_mul_f32 v[172:173], v[184:185], v[172:173]
	v_lshlrev_b32_e32 v200, 16, v174
	v_and_b32_e32 v201, 0xffff0000, v174
	v_lshlrev_b32_e32 v174, 16, v175
	v_and_b32_e32 v175, 0xffff0000, v175
	v_pk_mul_f32 v[200:201], v[178:179], v[200:201]
	v_pk_mul_f32 v[174:175], v[180:181], v[174:175]
	v_pk_fma_f32 v[112:113], v[112:113], v[100:101], v[172:173]
	v_pk_fma_f32 v[110:111], v[110:111], v[98:99], v[176:177]
	v_pk_fma_f32 v[108:109], v[108:109], v[96:97], v[174:175]
	v_pk_fma_f32 v[106:107], v[106:107], v[94:95], v[200:201]
	v_pk_mul_f32 v[174:175], v[186:187], v[112:113]
	v_pk_mul_f32 v[172:173], v[188:189], v[110:111]
	v_pk_mul_f32 v[176:177], v[190:191], v[108:109]
	v_pk_mul_f32 v[200:201], v[192:193], v[106:107]
	v_cvt_pk_bf16_f32 v172, v172, v173
	v_cvt_pk_bf16_f32 v173, v174, v175
	s_nop 0
	v_cvt_pk_bf16_f32 v174, v200, v201
	v_cvt_pk_bf16_f32 v175, v176, v177
	global_store_dwordx4 v[136:137], v[172:175], off
	v_lshl_add_u64 v[136:137], v[164:165], 0, s[34:35]
	s_nop 0
	v_lshl_add_u64 v[172:173], v[136:137], 0, v[166:167]
	v_lshlrev_b64 v[176:177], 1, v[172:173]
	v_lshl_add_u64 v[172:173], s[12:13], 0, v[176:177]
	v_lshl_add_u64 v[176:177], s[16:17], 0, v[176:177]
	s_nop 1
	v_mov_b32_e32 v172, v236
	v_mov_b32_e32 v173, v237
	v_mov_b32_e32 v174, v238
	v_mov_b32_e32 v175, v239
	v_lshlrev_b32_e32 v200, 16, v172
	v_and_b32_e32 v201, 0xffff0000, v172
	v_lshlrev_b32_e32 v172, 16, v173
	v_and_b32_e32 v173, 0xffff0000, v173
	v_pk_mul_f32 v[200:201], v[182:183], v[200:201]
	v_pk_mul_f32 v[172:173], v[184:185], v[172:173]
	v_lshlrev_b32_e32 v202, 16, v174
	v_and_b32_e32 v203, 0xffff0000, v174
	v_lshlrev_b32_e32 v174, 16, v175
	v_and_b32_e32 v175, 0xffff0000, v175
	v_pk_fma_f32 v[102:103], v[102:103], v[98:99], v[200:201]
	v_pk_mul_f32 v[202:203], v[178:179], v[202:203]
	v_pk_mul_f32 v[174:175], v[180:181], v[174:175]
	v_pk_fma_f32 v[104:105], v[104:105], v[100:101], v[172:173]
	v_pk_mul_f32 v[172:173], v[188:189], v[102:103]
	v_pk_fma_f32 v[92:93], v[92:93], v[96:97], v[174:175]
	v_pk_fma_f32 v[90:91], v[90:91], v[94:95], v[202:203]
	v_pk_mul_f32 v[174:175], v[186:187], v[104:105]
	v_cvt_pk_bf16_f32 v172, v172, v173
	v_pk_mul_f32 v[200:201], v[190:191], v[92:93]
	v_cvt_pk_bf16_f32 v173, v174, v175
	v_pk_mul_f32 v[202:203], v[192:193], v[90:91]
	s_nop 0
	v_cvt_pk_bf16_f32 v174, v202, v203
	v_cvt_pk_bf16_f32 v175, v200, v201
	global_store_dwordx4 v[176:177], v[172:175], off
	s_nop 1
	v_lshl_add_u64 v[172:173], v[164:165], 0, s[82:83]
	v_lshl_add_u64 v[174:175], v[172:173], 0, v[166:167]
	v_lshlrev_b64 v[200:201], 1, v[174:175]
	v_lshl_add_u64 v[174:175], s[12:13], 0, v[200:201]
;     __device__ __forceinline__ void operator()(const f32x4 (&acc)[2][2][4][2], const Unit& u, int wr, int wc, int fr, int fq) const {
;     ...
;         for (int bj = 0; bj < 2; ++bj) { const int col = col0 + bj * HALF;
;             const f32x4 g0 = *(const f32x4*)(gate + (size_t)bb * 6144 + col), g1 = *(const f32x4*)(gate + (size_t)bb * 6144 + col + 4);
;             f32x4 c0 = *(const f32x4*)(gain_c + col) * (*(const f32x4*)(sc_c + (size_t)bb * 6144 + col) + 1.f), c1 = *(const f32x4*)(gain_c + col + 4) * (*(const f32x4*)(sc_c + (size_t)bb * 6144 + col + 4) + 1.f);
; #pragma unroll
;             for (int e = 0; e < 4; ++e) { c0[e] = __builtin_amdgcn_rcpf(c0[e]); c1[e] = __builtin_amdgcn_rcpf(c1[e]); }
;             f32x4 n0 = c0, n1 = c1;
;             if (xs) { n0 = *(const f32x4*)(gain_n + col) * (*(const f32x4*)(sc_n + (size_t)bb * 6144 + col) + 1.f); n1 = *(const f32x4*)(gain_n + col + 4) * (*(const f32x4*)(sc_n + (size_t)bb * 6144 + col + 4) + 1.f); }
; #pragma unroll
;             for (int ai = 0; ai < 2; ++ai)
; #pragma unroll
;                 for (int m = 0; m < 4; ++m) { const size_t e0 = (size_t)(row0 + ai * HALF + m * 16) * 1024 + col;
;                     const u32x4 r = *(const u32x4*)(xs_in + e0);
;                     const f32x4 x0 = (f32x4){__builtin_bit_cast(float, r.x << 16), __builtin_bit_cast(float, r.x & 0xffff0000u), __builtin_bit_cast(float, r.y << 16), __builtin_bit_cast(float, r.y & 0xffff0000u)} * c0;
;                     const f32x4 x1 = (f32x4){__builtin_bit_cast(float, r.z << 16), __builtin_bit_cast(float, r.z & 0xffff0000u), __builtin_bit_cast(float, r.w << 16), __builtin_bit_cast(float, r.w & 0xffff0000u)} * c1;
;                     const f32x4 y0 = x0 + g0 * acc[ai][bj][m][0], y1 = x1 + g1 * acc[ai][bj][m][1];
;                     if (fout) { __builtin_nontemporal_store(y0, (f32x4*)(fout + e0)); __builtin_nontemporal_store(y1, (f32x4*)(fout + e0 + 4)); }
;                     if (xs) { const f32x4 z0 = y0 * n0, z1 = y1 * n1;
;                         u32x4 w; w.x = cvt_pk_bf16(z0[0], z0[1]); w.y = cvt_pk_bf16(z0[2], z0[3]); w.z = cvt_pk_bf16(z1[0], z1[1]); w.w = cvt_pk_bf16(z1[2], z1[3]);
;                         *(u32x4*)(xs + e0) = w;
;                         ssq[ai * 4 + m] += (y0[0] * y0[0] + y0[1] * y0[1]) + (y0[2] * y0[2] + y0[3] * y0[3]) + (y1[0] * y1[0] + y1[1] * y1[1]) + (y1[2] * y1[2] + y1[3] * y1[3]); } } }
	v_lshl_add_u64 v[200:201], s[16:17], 0, v[200:201]
	s_nop 1
	v_mov_b32_e32 v174, v244
	v_mov_b32_e32 v175, v245
	v_mov_b32_e32 v176, v246
	v_mov_b32_e32 v177, v247
	v_lshlrev_b32_e32 v202, 16, v174
	v_and_b32_e32 v203, 0xffff0000, v174
	v_lshlrev_b32_e32 v174, 16, v175
	v_and_b32_e32 v175, 0xffff0000, v175
	v_pk_mul_f32 v[202:203], v[182:183], v[202:203]
	v_pk_mul_f32 v[174:175], v[184:185], v[174:175]
	v_lshlrev_b32_e32 v210, 16, v176
	v_and_b32_e32 v211, 0xffff0000, v176
	v_lshlrev_b32_e32 v176, 16, v177
	v_and_b32_e32 v177, 0xffff0000, v177
	v_pk_fma_f32 v[86:87], v[86:87], v[98:99], v[202:203]
	v_pk_mul_f32 v[210:211], v[178:179], v[210:211]
	v_pk_mul_f32 v[176:177], v[180:181], v[176:177]
	v_pk_fma_f32 v[88:89], v[88:89], v[100:101], v[174:175]
	v_pk_mul_f32 v[174:175], v[188:189], v[86:87]
	v_pk_fma_f32 v[84:85], v[84:85], v[96:97], v[176:177]
	v_pk_fma_f32 v[82:83], v[82:83], v[94:95], v[210:211]
	v_pk_mul_f32 v[176:177], v[186:187], v[88:89]
	v_cvt_pk_bf16_f32 v174, v174, v175
	v_pk_mul_f32 v[202:203], v[190:191], v[84:85]
	v_cvt_pk_bf16_f32 v175, v176, v177
	v_pk_mul_f32 v[210:211], v[192:193], v[82:83]
	s_nop 0
	v_cvt_pk_bf16_f32 v176, v210, v211
	v_cvt_pk_bf16_f32 v177, v202, v203
	global_store_dwordx4 v[200:201], v[174:177], off
	s_nop 1
	v_lshl_add_u64 v[174:175], v[164:165], 0, s[84:85]
	v_lshl_add_u64 v[176:177], v[174:175], 0, v[166:167]
	v_lshlrev_b64 v[176:177], 1, v[176:177]
	v_lshl_add_u64 v[200:201], s[12:13], 0, v[176:177]
	v_lshl_add_u64 v[176:177], s[16:17], 0, v[176:177]
	s_nop 1
	v_mov_b32_e32 v200, v248
	v_mov_b32_e32 v201, v249
	v_mov_b32_e32 v202, v250
	v_mov_b32_e32 v203, v251
	v_lshlrev_b32_e32 v210, 16, v200
	v_and_b32_e32 v211, 0xffff0000, v200
	v_lshlrev_b32_e32 v200, 16, v201
	v_and_b32_e32 v201, 0xffff0000, v201
	v_pk_mul_f32 v[210:211], v[182:183], v[210:211]
	v_pk_mul_f32 v[200:201], v[184:185], v[200:201]
	v_lshlrev_b32_e32 v212, 16, v202
	v_and_b32_e32 v213, 0xffff0000, v202
	v_lshlrev_b32_e32 v202, 16, v203
	v_and_b32_e32 v203, 0xffff0000, v203
	v_pk_mul_f32 v[212:213], v[178:179], v[212:213]
	v_pk_mul_f32 v[202:203], v[180:181], v[202:203]
	v_pk_fma_f32 v[80:81], v[80:81], v[100:101], v[200:201]
	v_pk_fma_f32 v[78:79], v[78:79], v[98:99], v[210:211]
	v_pk_fma_f32 v[76:77], v[76:77], v[96:97], v[202:203]
	v_pk_fma_f32 v[74:75], v[74:75], v[94:95], v[212:213]
	v_pk_mul_f32 v[202:203], v[186:187], v[80:81]
	v_pk_mul_f32 v[200:201], v[188:189], v[78:79]
	v_pk_mul_f32 v[210:211], v[190:191], v[76:77]
	v_pk_mul_f32 v[212:213], v[192:193], v[74:75]
	v_cvt_pk_bf16_f32 v200, v200, v201
	v_cvt_pk_bf16_f32 v201, v202, v203
	s_nop 0
	v_cvt_pk_bf16_f32 v202, v212, v213
	v_cvt_pk_bf16_f32 v203, v210, v211
	global_store_dwordx4 v[176:177], v[200:203], off
	v_lshl_add_u64 v[176:177], v[164:165], 0, s[86:87]
	s_nop 0
	v_lshl_add_u64 v[200:201], v[176:177], 0, v[166:167]
	v_lshlrev_b64 v[210:211], 1, v[200:201]
	v_lshl_add_u64 v[200:201], s[12:13], 0, v[210:211]
	v_or_b32_e32 v166, 0x80, v166
	v_ashrrev_i32_e32 v167, 31, v166
	v_lshl_add_u64 v[164:165], v[164:165], 0, v[166:167]
	v_lshlrev_b64 v[164:165], 1, v[164:165]
	s_nop 1
	v_mov_b32_e32 v200, v252
	v_mov_b32_e32 v201, v253
	v_mov_b32_e32 v202, v254
	v_mov_b32_e32 v203, v255
	v_lshlrev_b32_e32 v212, 16, v200
	v_and_b32_e32 v213, 0xffff0000, v200
	v_lshlrev_b32_e32 v200, 16, v201
	v_and_b32_e32 v201, 0xffff0000, v201
	v_pk_mul_f32 v[184:185], v[184:185], v[200:201]
	v_lshlrev_b32_e32 v200, 16, v202
	v_and_b32_e32 v201, 0xffff0000, v202
	v_lshlrev_b32_e32 v202, 16, v203
	v_and_b32_e32 v203, 0xffff0000, v203
	v_pk_mul_f32 v[182:183], v[182:183], v[212:213]
	v_pk_mul_f32 v[180:181], v[180:181], v[202:203]
	v_pk_mul_f32 v[178:179], v[178:179], v[200:201]
	v_pk_fma_f32 v[100:101], v[72:73], v[100:101], v[184:185]
	v_pk_fma_f32 v[98:99], v[70:71], v[98:99], v[182:183]
	v_pk_fma_f32 v[96:97], v[68:69], v[96:97], v[180:181]
	v_pk_fma_f32 v[94:95], v[66:67], v[94:95], v[178:179]
	v_pk_mul_f32 v[68:69], v[186:187], v[100:101]
	v_pk_mul_f32 v[66:67], v[188:189], v[98:99]
	v_pk_mul_f32 v[70:71], v[190:191], v[96:97]
	v_pk_mul_f32 v[72:73], v[192:193], v[94:95]
	v_cvt_pk_bf16_f32 v66, v66, v67
	v_cvt_pk_bf16_f32 v67, v68, v69
	s_nop 0
	v_cvt_pk_bf16_f32 v68, v72, v73
	v_cvt_pk_bf16_f32 v69, v70, v71
	v_lshl_add_u64 v[70:71], s[16:17], 0, v[210:211]
	global_store_dwordx4 v[70:71], v[66:69], off
	global_load_dwordx4 v[70:73], v[168:169], off offset:512
	s_nop 0
	global_load_dwordx4 v[66:69], v[168:169], off offset:528
	global_load_dwordx4 v[178:181], v[170:171], off offset:528
	s_nop 0
	global_load_dwordx4 v[168:171], v[170:171], off offset:512
	s_nop 0
	global_load_dwordx4 v[182:185], v[152:153], off offset:528
	global_load_dwordx4 v[186:189], v[152:153], off offset:512
	global_load_dwordx4 v[220:223], v243, s[12:13] offset:256
	v_add_u32_e32 v241, 0x8000, v243
	global_load_dwordx4 v[224:227], v241, s[12:13] offset:256
	v_add_u32_e32 v240, 0x10000, v243
	global_load_dwordx4 v[228:231], v240, s[12:13] offset:256
	v_add_u32_e32 v241, 0x18000, v243
	global_load_dwordx4 v[232:235], v241, s[12:13] offset:256
	v_add_u32_e32 v240, 0x40000, v243
	global_load_dwordx4 v[236:239], v240, s[12:13] offset:256
	v_add_u32_e32 v241, 0x48000, v243
	global_load_dwordx4 v[244:247], v241, s[12:13] offset:256
	v_add_u32_e32 v240, 0x50000, v243
	global_load_dwordx4 v[248:251], v240, s[12:13] offset:256
	v_add_u32_e32 v241, 0x58000, v243
	global_load_dwordx4 v[252:255], v241, s[12:13] offset:256
	s_waitcnt vmcnt(0)
;     __device__ __forceinline__ void operator()(const f32x4 (&acc)[2][2][4][2], const Unit& u, int wr, int wc, int fr, int fq) const {
;     ...
;             const f32x4 g0 = *(const f32x4*)(gate + (size_t)bb * 6144 + col), g1 = *(const f32x4*)(gate + (size_t)bb * 6144 + col + 4);
;             f32x4 c0 = *(const f32x4*)(gain_c + col) * (*(const f32x4*)(sc_c + (size_t)bb * 6144 + col) + 1.f), c1 = *(const f32x4*)(gain_c + col + 4) * (*(const f32x4*)(sc_c + (size_t)bb * 6144 + col + 4) + 1.f);
; #pragma unroll
;             for (int e = 0; e < 4; ++e) { c0[e] = __builtin_amdgcn_rcpf(c0[e]); c1[e] = __builtin_amdgcn_rcpf(c1[e]); }
;             f32x4 n0 = c0, n1 = c1;
;             if (xs) { n0 = *(const f32x4*)(gain_n + col) * (*(const f32x4*)(sc_n + (size_t)bb * 6144 + col) + 1.f); n1 = *(const f32x4*)(gain_n + col + 4) * (*(const f32x4*)(sc_n + (size_t)bb * 6144 + col + 4) + 1.f); }
; #pragma unroll
;             for (int ai = 0; ai < 2; ++ai)
; #pragma unroll
;                 for (int m = 0; m < 4; ++m) { const size_t e0 = (size_t)(row0 + ai * HALF + m * 16) * 1024 + col;
;                     const u32x4 r = *(const u32x4*)(xs_in + e0);
;                     const f32x4 x0 = (f32x4){__builtin_bit_cast(float, r.x << 16), __builtin_bit_cast(float, r.x & 0xffff0000u), __builtin_bit_cast(float, r.y << 16), __builtin_bit_cast(float, r.y & 0xffff0000u)} * c0;
;                     const f32x4 x1 = (f32x4){__builtin_bit_cast(float, r.z << 16), __builtin_bit_cast(float, r.z & 0xffff0000u), __builtin_bit_cast(float, r.w << 16), __builtin_bit_cast(float, r.w & 0xffff0000u)} * c1;
;                     const f32x4 y0 = x0 + g0 * acc[ai][bj][m][0], y1 = x1 + g1 * acc[ai][bj][m][1];
;                     if (fout) { __builtin_nontemporal_store(y0, (f32x4*)(fout + e0)); __builtin_nontemporal_store(y1, (f32x4*)(fout + e0 + 4)); }
;                     if (xs) { const f32x4 z0 = y0 * n0, z1 = y1 * n1;
;                         u32x4 w; w.x = cvt_pk_bf16(z0[0], z0[1]); w.y = cvt_pk_bf16(z0[2], z0[3]); w.z = cvt_pk_bf16(z1[0], z1[1]); w.w = cvt_pk_bf16(z1[2], z1[3]);
;                         *(u32x4*)(xs + e0) = w;
;                         ssq[ai * 4 + m] += (y0[0] * y0[0] + y0[1] * y0[1]) + (y0[2] * y0[2] + y0[3] * y0[3]) + (y1[0] * y1[0] + y1[1] * y1[1]) + (y1[2] * y1[2] + y1[3] * y1[3]); } } }
;         if (xs) {
; #pragma unroll
	v_pk_add_f32 v[152:153], v[188:189], 1.0 op_sel_hi:[1,0]
	v_pk_add_f32 v[186:187], v[186:187], 1.0 op_sel_hi:[1,0]
	v_pk_mul_f32 v[188:189], v[170:171], v[152:153]
	v_pk_add_f32 v[170:171], v[182:183], 1.0 op_sel_hi:[1,0]
	v_pk_mul_f32 v[152:153], v[168:169], v[186:187]
	v_pk_mul_f32 v[178:179], v[178:179], v[170:171]
	v_pk_add_f32 v[168:169], v[184:185], 1.0 op_sel_hi:[1,0]
	v_rcp_f32_e32 v170, v152
	v_rcp_f32_e32 v152, v178
	v_rcp_f32_e32 v171, v153
	v_rcp_f32_e32 v153, v179
	v_rcp_f32_e32 v178, v188
	v_rcp_f32_e32 v179, v189
	global_load_dwordx4 v[182:185], v[162:163], off offset:528
	global_load_dwordx4 v[186:189], v[162:163], off offset:512
	global_load_dwordx4 v[190:193], v[150:151], off offset:528
	global_load_dwordx4 v[200:203], v[150:151], off offset:512
	v_pk_mul_f32 v[168:169], v[180:181], v[168:169]
	s_waitcnt vmcnt(1)
	v_pk_add_f32 v[180:181], v[192:193], 1.0 op_sel_hi:[1,0]
	s_waitcnt vmcnt(0)
	v_pk_add_f32 v[162:163], v[200:201], 1.0 op_sel_hi:[1,0]
	v_pk_mul_f32 v[180:181], v[184:185], v[180:181]
	v_pk_mul_f32 v[162:163], v[186:187], v[162:163]
	v_pk_add_f32 v[186:187], v[190:191], 1.0 op_sel_hi:[1,0]
	v_lshl_add_u64 v[184:185], s[12:13], 0, v[164:165]
	v_pk_mul_f32 v[182:183], v[182:183], v[186:187]
	v_rcp_f32_e32 v168, v168
	v_rcp_f32_e32 v169, v169
	v_pk_add_f32 v[150:151], v[202:203], 1.0 op_sel_hi:[1,0]
	v_lshl_add_u64 v[164:165], s[16:17], 0, v[164:165]
	v_pk_mul_f32 v[150:151], v[188:189], v[150:151]
	s_waitcnt vmcnt(0)
	s_nop 1
	v_mov_b32_e32 v184, v220
	v_mov_b32_e32 v185, v221
	v_mov_b32_e32 v186, v222
	v_mov_b32_e32 v187, v223
	v_lshlrev_b32_e32 v188, 16, v186
	v_and_b32_e32 v189, 0xffff0000, v186
	v_lshlrev_b32_e32 v186, 16, v187
	v_and_b32_e32 v187, 0xffff0000, v187
	v_pk_mul_f32 v[186:187], v[168:169], v[186:187]
	v_pk_mul_f32 v[188:189], v[152:153], v[188:189]
	v_pk_fma_f32 v[64:65], v[64:65], v[68:69], v[186:187]
	v_lshlrev_b32_e32 v186, 16, v184
	v_and_b32_e32 v187, 0xffff0000, v184
	v_lshlrev_b32_e32 v184, 16, v185
	v_and_b32_e32 v185, 0xffff0000, v185
	v_pk_mul_f32 v[186:187], v[170:171], v[186:187]
	v_pk_mul_f32 v[184:185], v[178:179], v[184:185]
	v_pk_fma_f32 v[186:187], v[58:59], v[70:71], v[186:187]
	v_pk_fma_f32 v[184:185], v[60:61], v[72:73], v[184:185]
	v_pk_mul_f32 v[58:59], v[162:163], v[186:187]
	v_pk_fma_f32 v[62:63], v[62:63], v[66:67], v[188:189]
	v_pk_mul_f32 v[60:61], v[150:151], v[184:185]
	v_cvt_pk_bf16_f32 v58, v58, v59
	v_pk_mul_f32 v[188:189], v[180:181], v[64:65]
	v_cvt_pk_bf16_f32 v59, v60, v61
	v_pk_mul_f32 v[190:191], v[182:183], v[62:63]
	s_nop 0
	v_cvt_pk_bf16_f32 v60, v190, v191
	v_cvt_pk_bf16_f32 v61, v188, v189
	global_store_dwordx4 v[164:165], v[58:61], off
	s_nop 1
	v_mul_f32_e32 v58, v187, v187
	v_mul_f32_e32 v59, v185, v185
	v_fmac_f32_e32 v58, v186, v186
	v_fmac_f32_e32 v59, v184, v184
	v_add_f32_e32 v58, v58, v59
	v_mul_f32_e32 v59, v63, v63
	v_fmac_f32_e32 v59, v62, v62
	v_add_f32_e32 v58, v59, v58
	v_mul_f32_e32 v59, v65, v65
	v_lshl_add_u64 v[60:61], v[130:131], 0, v[166:167]
	v_fmac_f32_e32 v59, v64, v64
	v_lshlrev_b64 v[64:65], 1, v[60:61]
	v_lshl_add_u64 v[60:61], s[12:13], 0, v[64:65]
	v_lshl_add_u64 v[64:65], s[16:17], 0, v[64:65]
	v_add_f32_e32 v58, v59, v58
	v_add_f32_e32 v58, v199, v58
	ds_swizzle_b32 v59, v58 offset:swizzle(SWAP,16)
	s_waitcnt lgkmcnt(0)
	v_add_f32_e32 v58, v58, v59
	ds_bpermute_b32 v59, v196, v58
	s_nop 1
	v_mov_b32_e32 v60, v224
	v_mov_b32_e32 v61, v225
	v_mov_b32_e32 v62, v226
	v_mov_b32_e32 v63, v227
	v_lshlrev_b32_e32 v130, 16, v60
	v_and_b32_e32 v131, 0xffff0000, v60
	v_lshlrev_b32_e32 v60, 16, v61
	v_and_b32_e32 v61, 0xffff0000, v61
	v_pk_mul_f32 v[130:131], v[170:171], v[130:131]
	v_pk_mul_f32 v[60:61], v[178:179], v[60:61]
	v_lshlrev_b32_e32 v164, 16, v62
	v_and_b32_e32 v165, 0xffff0000, v62
	v_lshlrev_b32_e32 v62, 16, v63
	v_and_b32_e32 v63, 0xffff0000, v63
	v_pk_fma_f32 v[54:55], v[54:55], v[70:71], v[130:131]
	v_pk_mul_f32 v[164:165], v[152:153], v[164:165]
	v_pk_mul_f32 v[62:63], v[168:169], v[62:63]
	v_pk_fma_f32 v[56:57], v[56:57], v[72:73], v[60:61]
	v_pk_mul_f32 v[60:61], v[162:163], v[54:55]
	v_pk_fma_f32 v[52:53], v[52:53], v[68:69], v[62:63]
	v_pk_fma_f32 v[50:51], v[50:51], v[66:67], v[164:165]
	v_pk_mul_f32 v[62:63], v[150:151], v[56:57]
	v_cvt_pk_bf16_f32 v60, v60, v61
	v_pk_mul_f32 v[130:131], v[180:181], v[52:53]
	v_cvt_pk_bf16_f32 v61, v62, v63
	v_pk_mul_f32 v[164:165], v[182:183], v[50:51]
	s_nop 0
	v_cvt_pk_bf16_f32 v62, v164, v165
	v_cvt_pk_bf16_f32 v63, v130, v131
	global_store_dwordx4 v[64:65], v[60:63], off
	s_nop 1
	v_lshl_add_u64 v[60:61], v[132:133], 0, v[166:167]
	v_lshlrev_b64 v[64:65], 1, v[60:61]
	v_lshl_add_u64 v[60:61], s[12:13], 0, v[64:65]
	v_lshl_add_u64 v[64:65], s[16:17], 0, v[64:65]
	s_nop 1
	v_mov_b32_e32 v60, v228
	v_mov_b32_e32 v61, v229
	v_mov_b32_e32 v62, v230
	v_mov_b32_e32 v63, v231
	v_lshlrev_b32_e32 v130, 16, v60
	v_and_b32_e32 v131, 0xffff0000, v60
	v_lshlrev_b32_e32 v60, 16, v61
	v_and_b32_e32 v61, 0xffff0000, v61
	v_pk_mul_f32 v[130:131], v[170:171], v[130:131]
	v_pk_mul_f32 v[60:61], v[178:179], v[60:61]
	v_lshlrev_b32_e32 v132, 16, v62
	v_and_b32_e32 v133, 0xffff0000, v62
	v_lshlrev_b32_e32 v62, 16, v63
	v_and_b32_e32 v63, 0xffff0000, v63
	v_pk_fma_f32 v[46:47], v[46:47], v[70:71], v[130:131]
	v_pk_mul_f32 v[132:133], v[152:153], v[132:133]
	v_pk_mul_f32 v[62:63], v[168:169], v[62:63]
	v_pk_fma_f32 v[48:49], v[48:49], v[72:73], v[60:61]
	v_pk_mul_f32 v[60:61], v[162:163], v[46:47]
	v_pk_fma_f32 v[44:45], v[44:45], v[68:69], v[62:63]
	v_pk_fma_f32 v[42:43], v[42:43], v[66:67], v[132:133]
	v_pk_mul_f32 v[62:63], v[150:151], v[48:49]
	v_cvt_pk_bf16_f32 v60, v60, v61
; __device__ __forceinline__ unsigned cvt_pk_bf16(float lo, float hi) { unsigned r; asm volatile("v_cvt_pk_bf16_f32 %0, %1, %2" : "=v"(r) : "v"(lo), "v"(hi)); return r; }
;     __device__ __forceinline__ void operator()(const f32x4 (&acc)[2][2][4][2], const Unit& u, int wr, int wc, int fr, int fq) const {
;     ...
;             for (int ai = 0; ai < 2; ++ai)
; #pragma unroll
;                 for (int m = 0; m < 4; ++m) { const size_t e0 = (size_t)(row0 + ai * HALF + m * 16) * 1024 + col;
;                     const u32x4 r = *(const u32x4*)(xs_in + e0);
;                     const f32x4 x0 = (f32x4){__builtin_bit_cast(float, r.x << 16), __builtin_bit_cast(float, r.x & 0xffff0000u), __builtin_bit_cast(float, r.y << 16), __builtin_bit_cast(float, r.y & 0xffff0000u)} * c0;
;                     const f32x4 x1 = (f32x4){__builtin_bit_cast(float, r.z << 16), __builtin_bit_cast(float, r.z & 0xffff0000u), __builtin_bit_cast(float, r.w << 16), __builtin_bit_cast(float, r.w & 0xffff0000u)} * c1;
;                     const f32x4 y0 = x0 + g0 * acc[ai][bj][m][0], y1 = x1 + g1 * acc[ai][bj][m][1];
;                     if (fout) { __builtin_nontemporal_store(y0, (f32x4*)(fout + e0)); __builtin_nontemporal_store(y1, (f32x4*)(fout + e0 + 4)); }
;                     if (xs) { const f32x4 z0 = y0 * n0, z1 = y1 * n1;
;                         u32x4 w; w.x = cvt_pk_bf16(z0[0], z0[1]); w.y = cvt_pk_bf16(z0[2], z0[3]); w.z = cvt_pk_bf16(z1[0], z1[1]); w.w = cvt_pk_bf16(z1[2], z1[3]);
;                         *(u32x4*)(xs + e0) = w;
;                         ssq[ai * 4 + m] += (y0[0] * y0[0] + y0[1] * y0[1]) + (y0[2] * y0[2] + y0[3] * y0[3]) + (y1[0] * y1[0] + y1[1] * y1[1]) + (y1[2] * y1[2] + y1[3] * y1[3]); } } }
	v_pk_mul_f32 v[130:131], v[180:181], v[44:45]
	v_cvt_pk_bf16_f32 v61, v62, v63
	v_pk_mul_f32 v[132:133], v[182:183], v[42:43]
	s_nop 0
	v_cvt_pk_bf16_f32 v62, v132, v133
	v_cvt_pk_bf16_f32 v63, v130, v131
	global_store_dwordx4 v[64:65], v[60:63], off
	s_nop 1
	v_lshl_add_u64 v[60:61], v[134:135], 0, v[166:167]
	v_lshlrev_b64 v[64:65], 1, v[60:61]
	v_lshl_add_u64 v[60:61], s[12:13], 0, v[64:65]
	v_lshl_add_u64 v[64:65], s[16:17], 0, v[64:65]
	s_nop 1
	v_mov_b32_e32 v60, v232
	v_mov_b32_e32 v61, v233
	v_mov_b32_e32 v62, v234
	v_mov_b32_e32 v63, v235
	v_lshlrev_b32_e32 v130, 16, v60
	v_and_b32_e32 v131, 0xffff0000, v60
	v_lshlrev_b32_e32 v60, 16, v61
	v_and_b32_e32 v61, 0xffff0000, v61
	v_pk_mul_f32 v[130:131], v[170:171], v[130:131]
	v_pk_mul_f32 v[60:61], v[178:179], v[60:61]
	v_lshlrev_b32_e32 v132, 16, v62
	v_and_b32_e32 v133, 0xffff0000, v62
	v_lshlrev_b32_e32 v62, 16, v63
	v_and_b32_e32 v63, 0xffff0000, v63
	v_pk_fma_f32 v[38:39], v[38:39], v[70:71], v[130:131]
	v_pk_mul_f32 v[132:133], v[152:153], v[132:133]
	v_pk_mul_f32 v[62:63], v[168:169], v[62:63]
	v_pk_fma_f32 v[40:41], v[40:41], v[72:73], v[60:61]
	v_pk_mul_f32 v[60:61], v[162:163], v[38:39]
	v_pk_fma_f32 v[36:37], v[36:37], v[68:69], v[62:63]
	v_pk_fma_f32 v[34:35], v[34:35], v[66:67], v[132:133]
	v_pk_mul_f32 v[62:63], v[150:151], v[40:41]
	v_cvt_pk_bf16_f32 v60, v60, v61
	v_pk_mul_f32 v[130:131], v[180:181], v[36:37]
	v_cvt_pk_bf16_f32 v61, v62, v63
	v_pk_mul_f32 v[132:133], v[182:183], v[34:35]
	s_nop 0
	v_cvt_pk_bf16_f32 v62, v132, v133
	v_cvt_pk_bf16_f32 v63, v130, v131
	global_store_dwordx4 v[64:65], v[60:63], off
	s_nop 1
	v_lshl_add_u64 v[60:61], v[136:137], 0, v[166:167]
	v_lshlrev_b64 v[64:65], 1, v[60:61]
	v_lshl_add_u64 v[60:61], s[12:13], 0, v[64:65]
	v_lshl_add_u64 v[64:65], s[16:17], 0, v[64:65]
	s_nop 1
	v_mov_b32_e32 v60, v236
	v_mov_b32_e32 v61, v237
	v_mov_b32_e32 v62, v238
	v_mov_b32_e32 v63, v239
	v_lshlrev_b32_e32 v130, 16, v60
	v_and_b32_e32 v131, 0xffff0000, v60
	v_lshlrev_b32_e32 v60, 16, v61
	v_and_b32_e32 v61, 0xffff0000, v61
	v_pk_mul_f32 v[130:131], v[170:171], v[130:131]
	v_pk_mul_f32 v[60:61], v[178:179], v[60:61]
	v_lshlrev_b32_e32 v132, 16, v62
	v_and_b32_e32 v133, 0xffff0000, v62
	v_lshlrev_b32_e32 v62, 16, v63
	v_and_b32_e32 v63, 0xffff0000, v63
	v_pk_fma_f32 v[30:31], v[30:31], v[70:71], v[130:131]
	v_pk_mul_f32 v[132:133], v[152:153], v[132:133]
	v_pk_mul_f32 v[62:63], v[168:169], v[62:63]
	v_pk_fma_f32 v[32:33], v[32:33], v[72:73], v[60:61]
	v_pk_mul_f32 v[60:61], v[162:163], v[30:31]
	v_pk_fma_f32 v[28:29], v[28:29], v[68:69], v[62:63]
	v_pk_fma_f32 v[26:27], v[26:27], v[66:67], v[132:133]
	v_pk_mul_f32 v[62:63], v[150:151], v[32:33]
	v_cvt_pk_bf16_f32 v60, v60, v61
	v_pk_mul_f32 v[130:131], v[180:181], v[28:29]
	v_cvt_pk_bf16_f32 v61, v62, v63
	v_pk_mul_f32 v[132:133], v[182:183], v[26:27]
	s_nop 0
	v_cvt_pk_bf16_f32 v62, v132, v133
	v_cvt_pk_bf16_f32 v63, v130, v131
	global_store_dwordx4 v[64:65], v[60:63], off
	s_nop 1
	v_lshl_add_u64 v[60:61], v[172:173], 0, v[166:167]
	v_lshlrev_b64 v[64:65], 1, v[60:61]
	v_lshl_add_u64 v[60:61], s[12:13], 0, v[64:65]
	v_lshl_add_u64 v[64:65], s[16:17], 0, v[64:65]
	s_nop 1
	v_mov_b32_e32 v60, v244
	v_mov_b32_e32 v61, v245
	v_mov_b32_e32 v62, v246
	v_mov_b32_e32 v63, v247
	v_lshlrev_b32_e32 v130, 16, v60
	v_and_b32_e32 v131, 0xffff0000, v60
	v_lshlrev_b32_e32 v60, 16, v61
	v_and_b32_e32 v61, 0xffff0000, v61
	v_pk_mul_f32 v[130:131], v[170:171], v[130:131]
	v_pk_mul_f32 v[60:61], v[178:179], v[60:61]
	v_lshlrev_b32_e32 v132, 16, v62
	v_and_b32_e32 v133, 0xffff0000, v62
	v_lshlrev_b32_e32 v62, 16, v63
	v_and_b32_e32 v63, 0xffff0000, v63
	v_pk_fma_f32 v[22:23], v[22:23], v[70:71], v[130:131]
; __device__ __forceinline__ unsigned cvt_pk_bf16(float lo, float hi) { unsigned r; asm volatile("v_cvt_pk_bf16_f32 %0, %1, %2" : "=v"(r) : "v"(lo), "v"(hi)); return r; }
;     __device__ __forceinline__ void operator()(const f32x4 (&acc)[2][2][4][2], const Unit& u, int wr, int wc, int fr, int fq) const {
;     ...
;             for (int ai = 0; ai < 2; ++ai)
; #pragma unroll
;                 for (int m = 0; m < 4; ++m) { const size_t e0 = (size_t)(row0 + ai * HALF + m * 16) * 1024 + col;
;                     const u32x4 r = *(const u32x4*)(xs_in + e0);
;                     const f32x4 x0 = (f32x4){__builtin_bit_cast(float, r.x << 16), __builtin_bit_cast(float, r.x & 0xffff0000u), __builtin_bit_cast(float, r.y << 16), __builtin_bit_cast(float, r.y & 0xffff0000u)} * c0;
;                     const f32x4 x1 = (f32x4){__builtin_bit_cast(float, r.z << 16), __builtin_bit_cast(float, r.z & 0xffff0000u), __builtin_bit_cast(float, r.w << 16), __builtin_bit_cast(float, r.w & 0xffff0000u)} * c1;
;                     const f32x4 y0 = x0 + g0 * acc[ai][bj][m][0], y1 = x1 + g1 * acc[ai][bj][m][1];
;                     if (fout) { __builtin_nontemporal_store(y0, (f32x4*)(fout + e0)); __builtin_nontemporal_store(y1, (f32x4*)(fout + e0 + 4)); }
;                     if (xs) { const f32x4 z0 = y0 * n0, z1 = y1 * n1;
;                         u32x4 w; w.x = cvt_pk_bf16(z0[0], z0[1]); w.y = cvt_pk_bf16(z0[2], z0[3]); w.z = cvt_pk_bf16(z1[0], z1[1]); w.w = cvt_pk_bf16(z1[2], z1[3]);
;                         *(u32x4*)(xs + e0) = w;
;                         ssq[ai * 4 + m] += (y0[0] * y0[0] + y0[1] * y0[1]) + (y0[2] * y0[2] + y0[3] * y0[3]) + (y1[0] * y1[0] + y1[1] * y1[1]) + (y1[2] * y1[2] + y1[3] * y1[3]); } } }
;         if (xs) {
; #pragma unroll
;             for (int i = 0; i < 8; ++i) { float q = ssq[i];
;                 q += __builtin_bit_cast(float, __builtin_amdgcn_ds_swizzle(__builtin_bit_cast(int, q), (16 << 10) | 0x1f));
;                 q += __builtin_bit_cast(float, __builtin_amdgcn_ds_bpermute(x32, __builtin_bit_cast(int, q)));
;                 if (fq == 0) atomicAdd(rowsq + row0 + (i >> 2) * HALF + (i & 3) * 16, (unsigned long long)(q * 4294967296.f)); } }
	v_pk_mul_f32 v[132:133], v[152:153], v[132:133]
	v_pk_mul_f32 v[62:63], v[168:169], v[62:63]
	v_pk_fma_f32 v[24:25], v[24:25], v[72:73], v[60:61]
	v_pk_mul_f32 v[60:61], v[162:163], v[22:23]
	v_pk_fma_f32 v[20:21], v[20:21], v[68:69], v[62:63]
	v_pk_fma_f32 v[18:19], v[18:19], v[66:67], v[132:133]
	v_pk_mul_f32 v[62:63], v[150:151], v[24:25]
	v_cvt_pk_bf16_f32 v60, v60, v61
	v_pk_mul_f32 v[130:131], v[180:181], v[20:21]
	v_cvt_pk_bf16_f32 v61, v62, v63
	v_pk_mul_f32 v[132:133], v[182:183], v[18:19]
	s_nop 0
	v_cvt_pk_bf16_f32 v62, v132, v133
	v_cvt_pk_bf16_f32 v63, v130, v131
	global_store_dwordx4 v[64:65], v[60:63], off
	s_nop 1
	v_lshl_add_u64 v[60:61], v[174:175], 0, v[166:167]
	v_lshlrev_b64 v[64:65], 1, v[60:61]
	v_lshl_add_u64 v[60:61], s[12:13], 0, v[64:65]
	v_lshl_add_u64 v[64:65], s[16:17], 0, v[64:65]
	s_nop 1
	v_mov_b32_e32 v60, v248
	v_mov_b32_e32 v61, v249
	v_mov_b32_e32 v62, v250
	v_mov_b32_e32 v63, v251
	v_lshlrev_b32_e32 v130, 16, v60
	v_and_b32_e32 v131, 0xffff0000, v60
	v_lshlrev_b32_e32 v60, 16, v61
	v_and_b32_e32 v61, 0xffff0000, v61
	v_pk_mul_f32 v[130:131], v[170:171], v[130:131]
	v_pk_mul_f32 v[60:61], v[178:179], v[60:61]
	v_lshlrev_b32_e32 v132, 16, v62
	v_and_b32_e32 v133, 0xffff0000, v62
	v_lshlrev_b32_e32 v62, 16, v63
	v_and_b32_e32 v63, 0xffff0000, v63
	v_pk_fma_f32 v[14:15], v[14:15], v[70:71], v[130:131]
	v_pk_mul_f32 v[132:133], v[152:153], v[132:133]
	v_pk_mul_f32 v[62:63], v[168:169], v[62:63]
	v_pk_fma_f32 v[16:17], v[16:17], v[72:73], v[60:61]
	v_pk_mul_f32 v[60:61], v[162:163], v[14:15]
	v_pk_fma_f32 v[12:13], v[12:13], v[68:69], v[62:63]
	v_pk_fma_f32 v[10:11], v[10:11], v[66:67], v[132:133]
	v_pk_mul_f32 v[62:63], v[150:151], v[16:17]
	v_cvt_pk_bf16_f32 v60, v60, v61
	v_pk_mul_f32 v[130:131], v[180:181], v[12:13]
	v_cvt_pk_bf16_f32 v61, v62, v63
	v_pk_mul_f32 v[132:133], v[182:183], v[10:11]
	s_nop 0
	v_cvt_pk_bf16_f32 v62, v132, v133
	v_cvt_pk_bf16_f32 v63, v130, v131
	global_store_dwordx4 v[64:65], v[60:63], off
	s_nop 1
	v_lshl_add_u64 v[60:61], v[176:177], 0, v[166:167]
	v_lshlrev_b64 v[64:65], 1, v[60:61]
	v_lshl_add_u64 v[60:61], s[12:13], 0, v[64:65]
	v_lshl_add_u64 v[64:65], s[16:17], 0, v[64:65]
	s_nop 1
	v_mov_b32_e32 v60, v252
	v_mov_b32_e32 v61, v253
	v_mov_b32_e32 v62, v254
	v_mov_b32_e32 v63, v255
	v_lshlrev_b32_e32 v130, 16, v60
	v_and_b32_e32 v131, 0xffff0000, v60
	v_lshlrev_b32_e32 v60, 16, v61
	v_and_b32_e32 v61, 0xffff0000, v61
	v_pk_mul_f32 v[130:131], v[170:171], v[130:131]
	v_pk_mul_f32 v[60:61], v[178:179], v[60:61]
	v_lshlrev_b32_e32 v132, 16, v62
	v_and_b32_e32 v133, 0xffff0000, v62
	v_lshlrev_b32_e32 v62, 16, v63
	v_and_b32_e32 v63, 0xffff0000, v63
	v_pk_mul_f32 v[132:133], v[152:153], v[132:133]
	v_pk_mul_f32 v[62:63], v[168:169], v[62:63]
	v_pk_fma_f32 v[8:9], v[8:9], v[72:73], v[60:61]
	v_pk_fma_f32 v[6:7], v[6:7], v[70:71], v[130:131]
	v_pk_fma_f32 v[4:5], v[4:5], v[68:69], v[62:63]
	v_pk_fma_f32 v[2:3], v[2:3], v[66:67], v[132:133]
	v_pk_mul_f32 v[62:63], v[150:151], v[8:9]
	v_pk_mul_f32 v[60:61], v[162:163], v[6:7]
	v_pk_mul_f32 v[66:67], v[180:181], v[4:5]
	v_pk_mul_f32 v[68:69], v[182:183], v[2:3]
	v_cvt_pk_bf16_f32 v60, v60, v61
	v_cvt_pk_bf16_f32 v61, v62, v63
	s_nop 0
	v_cvt_pk_bf16_f32 v62, v68, v69
	v_cvt_pk_bf16_f32 v63, v66, v67
	global_store_dwordx4 v[64:65], v[60:63], off
	s_and_saveexec_b64 s[34:35], s[4:5]
	s_cbranch_execz .LBB0_663
	s_waitcnt lgkmcnt(0)
	v_add_f32_e32 v58, v58, v59
	v_mul_f32_e32 v58, 0x4f800000, v58
	v_trunc_f32_e32 v58, v58
	v_mul_f32_e32 v59, 0x2f800000, v58
	v_floor_f32_e32 v59, v59
	v_fmac_f32_e32 v58, 0xcf800000, v59
	v_cvt_u32_f32_e32 v58, v58
	v_cvt_u32_f32_e32 v59, v59
	v_lshl_add_u64 v[60:61], v[148:149], 3, s[20:21]
	global_atomic_add_x2 v[60:61], v[58:59], off
